# scan staging: touch-ahead dummy loads 8 chunks ahead (translation / cache warm-up)
# speedup vs baseline: 1.0038x; 1.0038x over previous
.LBB0_626:
	s_or_b64 exec, exec, s[0:1]
	v_lshlrev_b32_e32 v4, 16, v67
	v_mul_f32_e32 v4, 0xbfb8aa3b, v4
	v_exp_f32_e32 v4, v4
	s_or_b32 s0, s30, 7
	v_lshlrev_b32_e32 v0, 16, v31
	v_lshlrev_b32_e32 v2, 16, v70
	v_mul_f32_e32 v0, v41, v0
	v_add_f32_e32 v5, -1.0, v2
	s_lshl_b32 s27, s0, 8
	v_mul_f32_e32 v0, v32, v0
	v_fma_f32 v5, v42, v5, 1.0
	s_add_i32 s1, s36, s27
	v_mul_f32_e32 v3, v5, v3
	v_mul_f32_e32 v0, v4, v0
	v_lshl_add_u32 v5, v37, 2, s1
	ds_write2st64_b32 v5, v0, v4 offset1:16
	v_mul_f32_e32 v0, v1, v2
	ds_write2st64_b32 v5, v0, v3 offset0:32 offset1:48
	v_lshlrev_b32_e32 v0, 16, v27
	v_lshlrev_b32_e32 v1, 16, v62
	s_lshl_b32 s25, s0, 3
	ds_write2st64_b32 v5, v0, v1 offset0:64 offset1:80
	s_and_saveexec_b64 s[0:1], s[2:3]
	s_add_i32 s36, s36, s25
	v_mov_b32_e32 v0, v29
	v_mov_b32_e32 v1, v30
	v_mov_b32_e32 v2, s36
	ds_write_b64 v2, v[0:1] offset:24576
	s_or_b64 exec, exec, s[0:1]
	s_or_b32 s0, s31, 16
	v_readlane_b32 s50, v253, 20
	s_add_i32 s48, s0, s50
	v_readlane_b32 s46, v254, 25
	s_lshl_b64 s[36:37], s[48:49], 10
	v_or3_b32 v1, s37, 0, 0
	v_mov_b32_e32 v28, s46
	v_or3_b32 v0, s36, v28, v37
	v_lshlrev_b64 v[0:1], 1, v[0:1]
	v_lshl_add_u64 v[2:3], s[4:5], 0, v[0:1]
	global_load_ushort v43, v[2:3], off
	v_lshl_add_u64 v[2:3], s[8:9], 0, v[0:1]
	s_lshl_b64 s[36:37], s[48:49], 8
	global_load_ushort v45, v[2:3], off
	v_lshl_add_u64 v[2:3], s[10:11], 0, v[0:1]
	s_add_u32 s36, s16, s36
	global_load_ushort v44, v[2:3], off
	v_lshl_add_u64 v[2:3], s[6:7], 0, v[0:1]
	v_lshl_add_u64 v[0:1], s[12:13], 0, v[0:1]
	s_addc_u32 s37, s17, s37
	v_readlane_b32 s47, v254, 26
	global_load_ushort v46, v[2:3], off
	global_load_ushort v49, v[0:1], off
	s_mov_b32 s40, 1
	global_load_dwordx4 v[0:3], v177, s[36:37]
	s_or_b32 s36, s48, 1
	s_mov_b32 s37, s49
	s_lshl_b64 s[46:47], s[36:37], 10
	v_or3_b32 v5, s47, 0, 0
	v_or3_b32 v4, s46, v28, v37
	v_lshlrev_b64 v[4:5], 1, v[4:5]
	v_lshl_add_u64 v[6:7], s[4:5], 0, v[4:5]
	global_load_ushort v3, v[6:7], off
	v_lshl_add_u64 v[6:7], s[8:9], 0, v[4:5]
	s_lshl_b64 s[36:37], s[36:37], 8
	global_load_ushort v52, v[6:7], off
	v_lshl_add_u64 v[6:7], s[10:11], 0, v[4:5]
	s_add_u32 s36, s16, s36
	global_load_ushort v47, v[6:7], off
	v_lshl_add_u64 v[6:7], s[6:7], 0, v[4:5]
	v_lshl_add_u64 v[4:5], s[12:13], 0, v[4:5]
	s_addc_u32 s37, s17, s37
	global_load_ushort v50, v[6:7], off
	global_load_ushort v53, v[4:5], off
	v_lshlrev_b32_e32 v36, 1, v36
	global_load_dwordx4 v[4:7], v177, s[36:37]
	s_or_b32 s36, s48, 2
	s_mov_b32 s37, s49
	s_lshl_b64 s[46:47], s[36:37], 10
	v_or3_b32 v9, s47, 0, 0
	v_or3_b32 v8, s46, v28, v37
	v_lshlrev_b64 v[8:9], 1, v[8:9]
	v_lshl_add_u64 v[10:11], s[4:5], 0, v[8:9]
	global_load_ushort v7, v[10:11], off
	v_lshl_add_u64 v[10:11], s[8:9], 0, v[8:9]
	s_lshl_b64 s[36:37], s[36:37], 8
	global_load_ushort v60, v[10:11], off
	v_lshl_add_u64 v[10:11], s[10:11], 0, v[8:9]
	s_add_u32 s36, s16, s36
	global_load_ushort v48, v[10:11], off
	v_lshl_add_u64 v[10:11], s[6:7], 0, v[8:9]
	v_lshl_add_u64 v[8:9], s[12:13], 0, v[8:9]
	s_addc_u32 s37, s17, s37
	global_load_ushort v51, v[10:11], off
	global_load_ushort v55, v[8:9], off
	s_nop 0
	global_load_dwordx4 v[8:11], v177, s[36:37]
	s_or_b32 s36, s48, 3
	s_mov_b32 s37, s49
	s_lshl_b64 s[46:47], s[36:37], 10
	v_or3_b32 v13, s47, 0, 0
	v_or3_b32 v12, s46, v28, v37
	v_lshlrev_b64 v[12:13], 1, v[12:13]
	v_lshl_add_u64 v[14:15], s[4:5], 0, v[12:13]
	global_load_ushort v11, v[14:15], off
	v_lshl_add_u64 v[14:15], s[8:9], 0, v[12:13]
	s_lshl_b64 s[36:37], s[36:37], 8
	global_load_ushort v64, v[14:15], off
	v_lshl_add_u64 v[14:15], s[10:11], 0, v[12:13]
	s_add_u32 s36, s16, s36
	global_load_ushort v54, v[14:15], off
	v_lshl_add_u64 v[14:15], s[6:7], 0, v[12:13]
	v_lshl_add_u64 v[12:13], s[12:13], 0, v[12:13]
	s_addc_u32 s37, s17, s37
	global_load_ushort v57, v[14:15], off
	global_load_ushort v58, v[12:13], off
	s_nop 0
	global_load_dwordx4 v[12:15], v177, s[36:37]
	s_or_b32 s36, s48, 4
	s_mov_b32 s37, s49
	s_lshl_b64 s[46:47], s[36:37], 10
	v_or3_b32 v17, s47, 0, 0
	v_or3_b32 v16, s46, v28, v37
	v_lshlrev_b64 v[16:17], 1, v[16:17]
	v_lshl_add_u64 v[18:19], s[4:5], 0, v[16:17]
	global_load_ushort v15, v[18:19], off
	v_lshl_add_u64 v[18:19], s[8:9], 0, v[16:17]
	s_lshl_b64 s[36:37], s[36:37], 8
	global_load_ushort v67, v[18:19], off
	v_lshl_add_u64 v[18:19], s[10:11], 0, v[16:17]
	s_add_u32 s36, s16, s36
	global_load_ushort v56, v[18:19], off
	v_lshl_add_u64 v[18:19], s[6:7], 0, v[16:17]
	v_lshl_add_u64 v[16:17], s[12:13], 0, v[16:17]
	s_addc_u32 s37, s17, s37
	global_load_ushort v61, v[18:19], off
	global_load_ushort v63, v[16:17], off
	s_nop 0
	global_load_dwordx4 v[16:19], v177, s[36:37]
	s_or_b32 s36, s48, 5
	s_mov_b32 s37, s49
	s_lshl_b64 s[46:47], s[36:37], 10
	v_or3_b32 v21, s47, 0, 0
	v_or3_b32 v20, s46, v28, v37
	v_lshlrev_b64 v[20:21], 1, v[20:21]
	v_lshl_add_u64 v[22:23], s[4:5], 0, v[20:21]
	global_load_ushort v19, v[22:23], off
	v_lshl_add_u64 v[22:23], s[8:9], 0, v[20:21]
	s_lshl_b64 s[36:37], s[36:37], 8
	global_load_ushort v72, v[22:23], off
	v_lshl_add_u64 v[22:23], s[10:11], 0, v[20:21]
	s_add_u32 s36, s16, s36
	global_load_ushort v59, v[22:23], off
	v_lshl_add_u64 v[22:23], s[6:7], 0, v[20:21]
	v_lshl_add_u64 v[20:21], s[12:13], 0, v[20:21]
	s_addc_u32 s37, s17, s37
	global_load_ushort v62, v[22:23], off
	global_load_ushort v66, v[20:21], off
	s_nop 0
	global_load_dwordx4 v[20:23], v177, s[36:37]
	s_or_b32 s36, s48, 6
	s_mov_b32 s37, s49
	s_lshl_b64 s[46:47], s[36:37], 10
	v_or3_b32 v25, s47, 0, 0
	v_or3_b32 v24, s46, v28, v37
	v_lshlrev_b64 v[24:25], 1, v[24:25]
	v_lshl_add_u64 v[26:27], s[4:5], 0, v[24:25]
	global_load_ushort v23, v[26:27], off
	v_lshl_add_u64 v[26:27], s[8:9], 0, v[24:25]
	s_lshl_b64 s[36:37], s[36:37], 8
	global_load_ushort v74, v[26:27], off
	v_lshl_add_u64 v[26:27], s[10:11], 0, v[24:25]
	s_add_u32 s36, s16, s36
	global_load_ushort v65, v[26:27], off
	v_lshl_add_u64 v[26:27], s[6:7], 0, v[24:25]
	v_lshl_add_u64 v[24:25], s[12:13], 0, v[24:25]
	s_addc_u32 s37, s17, s37
	s_or_b32 s48, s48, 7
	global_load_ushort v69, v[26:27], off
	global_load_ushort v71, v[24:25], off
	s_nop 0
	global_load_dwordx4 v[24:27], v177, s[36:37]
	s_lshl_b64 s[36:37], s[48:49], 10
	v_or3_b32 v29, s37, 0, 0
	v_or3_b32 v28, s36, v28, v37
	s_lshl_b64 s[36:37], s[48:49], 8
	s_add_u32 s36, s16, s36
	s_addc_u32 s37, s17, s37
	s_min_u32 s0, s0, 0x1ff7
	v_lshlrev_b64 v[28:29], 1, v[28:29]
	s_add_i32 s48, s0, s51
	v_lshl_add_u64 v[30:31], s[4:5], 0, v[28:29]
	s_lshl_b64 s[0:1], s[48:49], 11
	global_load_ushort v27, v[30:31], off
	v_lshl_add_u64 v[30:31], s[8:9], 0, v[28:29]
	s_add_u32 s0, s8, s0
	global_load_ushort v75, v[30:31], off
	v_lshl_add_u64 v[30:31], s[10:11], 0, v[28:29]
	s_addc_u32 s1, s9, s1
	global_load_ushort v68, v[30:31], off
	v_lshl_add_u64 v[30:31], s[6:7], 0, v[28:29]
	v_lshl_add_u64 v[28:29], s[12:13], 0, v[28:29]
	s_add_u32 s0, s0, s33
	global_load_ushort v70, v[30:31], off
	global_load_ushort v73, v[28:29], off
	s_addc_u32 s1, s1, 0
	global_load_dwordx4 v[28:31], v177, s[36:37]
	global_load_ushort v31, v176, s[0:1]
	s_lshl_b64 s[0:1], s[48:49], 8
	s_add_u32 s0, s16, s0
	s_addc_u32 s1, s17, s1
	global_load_dwordx4 v[32:35], v177, s[0:1]
	s_waitcnt lgkmcnt(0)
	s_barrier
	s_add_u32 s0, s8, s33
	s_addc_u32 s1, s9, 0
	s_add_i32 s29, s29, s30
	v_lshl_add_u64 v[38:39], s[0:1], 0, v[176:177]
	s_lshl_b32 s37, s28, 6
	s_lshl_b32 s36, s34, 3
	s_lshl_b32 s35, s35, 3
	s_lshl_b32 s34, s41, 3
	s_lshl_b32 s33, s42, 3
	s_lshl_b32 s31, s44, 3
	s_lshl_b32 s28, s45, 3
	s_add_i32 s30, s29, s50
	s_mov_b32 s41, 0
	s_add_i32 s1, s30, s41
	s_add_i32 s48, s1, 32
	s_lshl_b64 s[44:45], s[48:49], 11
	v_or_b32_e32 v100, s44, v36
	v_mov_b32_e32 v101, s45
	s_add_i32 s0, s29, s41
	v_lshl_add_u64 v[102:103], s[4:5], 0, v[100:101]
	s_add_i32 s0, s0, 32
	global_load_ushort v143, v[102:103], off
	v_lshl_add_u64 v[102:103], s[8:9], 0, v[100:101]
	s_lshl_b64 s[44:45], s[48:49], 8
	global_load_ushort v145, v[102:103], off
	v_lshl_add_u64 v[102:103], s[10:11], 0, v[100:101]
	s_add_u32 s44, s16, s44
	global_load_ushort v144, v[102:103], off
	v_lshl_add_u64 v[102:103], s[6:7], 0, v[100:101]
	v_lshl_add_u64 v[100:101], s[12:13], 0, v[100:101]
	s_addc_u32 s45, s17, s45
	s_add_i32 s48, s1, 33
	global_load_ushort v146, v[102:103], off
	global_load_ushort v149, v[100:101], off
	s_nop 0
	global_load_dwordx4 v[100:103], v177, s[44:45]
	s_lshl_b64 s[44:45], s[48:49], 11
	v_or_b32_e32 v104, s44, v36
	v_mov_b32_e32 v105, s45
	v_lshl_add_u64 v[106:107], s[4:5], 0, v[104:105]
	global_load_ushort v103, v[106:107], off
	v_lshl_add_u64 v[106:107], s[8:9], 0, v[104:105]
	s_lshl_b64 s[44:45], s[48:49], 8
	global_load_ushort v152, v[106:107], off
	v_lshl_add_u64 v[106:107], s[10:11], 0, v[104:105]
	s_add_u32 s44, s16, s44
	global_load_ushort v147, v[106:107], off
	v_lshl_add_u64 v[106:107], s[6:7], 0, v[104:105]
	v_lshl_add_u64 v[104:105], s[12:13], 0, v[104:105]
	s_addc_u32 s45, s17, s45
	s_add_i32 s48, s1, 34
	global_load_ushort v150, v[106:107], off
	global_load_ushort v153, v[104:105], off
	s_nop 0
	global_load_dwordx4 v[104:107], v177, s[44:45]
	s_lshl_b64 s[44:45], s[48:49], 11
	v_or_b32_e32 v108, s44, v36
	v_mov_b32_e32 v109, s45
	v_lshl_add_u64 v[110:111], s[4:5], 0, v[108:109]
	global_load_ushort v107, v[110:111], off
	v_lshl_add_u64 v[110:111], s[8:9], 0, v[108:109]
	s_lshl_b64 s[44:45], s[48:49], 8
	global_load_ushort v160, v[110:111], off
	v_lshl_add_u64 v[110:111], s[10:11], 0, v[108:109]
	s_add_u32 s44, s16, s44
	global_load_ushort v148, v[110:111], off
	v_lshl_add_u64 v[110:111], s[6:7], 0, v[108:109]
	v_lshl_add_u64 v[108:109], s[12:13], 0, v[108:109]
	s_addc_u32 s45, s17, s45
	s_add_i32 s48, s1, 35
	global_load_ushort v151, v[110:111], off
	global_load_ushort v155, v[108:109], off
	s_nop 0
	global_load_dwordx4 v[108:111], v177, s[44:45]
	s_lshl_b64 s[44:45], s[48:49], 11
	v_or_b32_e32 v112, s44, v36
	v_mov_b32_e32 v113, s45
	v_lshl_add_u64 v[114:115], s[4:5], 0, v[112:113]
	global_load_ushort v111, v[114:115], off
	v_lshl_add_u64 v[114:115], s[8:9], 0, v[112:113]
	s_lshl_b64 s[44:45], s[48:49], 8
	global_load_ushort v164, v[114:115], off
	v_lshl_add_u64 v[114:115], s[10:11], 0, v[112:113]
	s_add_u32 s44, s16, s44
	global_load_ushort v154, v[114:115], off
	v_lshl_add_u64 v[114:115], s[6:7], 0, v[112:113]
	v_lshl_add_u64 v[112:113], s[12:13], 0, v[112:113]
	s_addc_u32 s45, s17, s45
	s_add_i32 s48, s1, 36
	global_load_ushort v157, v[114:115], off
	global_load_ushort v158, v[112:113], off
	s_nop 0
	global_load_dwordx4 v[112:115], v177, s[44:45]
	s_lshl_b64 s[44:45], s[48:49], 11
	v_or_b32_e32 v116, s44, v36
	v_mov_b32_e32 v117, s45
	v_lshl_add_u64 v[118:119], s[4:5], 0, v[116:117]
	global_load_ushort v115, v[118:119], off
	v_lshl_add_u64 v[118:119], s[8:9], 0, v[116:117]
	s_lshl_b64 s[44:45], s[48:49], 8
	global_load_ushort v167, v[118:119], off
	v_lshl_add_u64 v[118:119], s[10:11], 0, v[116:117]
	s_add_u32 s44, s16, s44
	global_load_ushort v156, v[118:119], off
	v_lshl_add_u64 v[118:119], s[6:7], 0, v[116:117]
	v_lshl_add_u64 v[116:117], s[12:13], 0, v[116:117]
	s_addc_u32 s45, s17, s45
	s_add_i32 s48, s1, 37
	global_load_ushort v161, v[118:119], off
	global_load_ushort v163, v[116:117], off
	s_nop 0
	global_load_dwordx4 v[116:119], v177, s[44:45]
	s_lshl_b64 s[44:45], s[48:49], 11
	v_or_b32_e32 v120, s44, v36
	v_mov_b32_e32 v121, s45
	v_lshl_add_u64 v[122:123], s[4:5], 0, v[120:121]
	global_load_ushort v119, v[122:123], off
	v_lshl_add_u64 v[122:123], s[8:9], 0, v[120:121]
	s_lshl_b64 s[44:45], s[48:49], 8
	global_load_ushort v172, v[122:123], off
	v_lshl_add_u64 v[122:123], s[10:11], 0, v[120:121]
	s_add_u32 s44, s16, s44
	global_load_ushort v159, v[122:123], off
	v_lshl_add_u64 v[122:123], s[6:7], 0, v[120:121]
	v_lshl_add_u64 v[120:121], s[12:13], 0, v[120:121]
	s_addc_u32 s45, s17, s45
	s_add_i32 s48, s1, 38
	global_load_ushort v162, v[122:123], off
	global_load_ushort v166, v[120:121], off
	s_nop 0
	global_load_dwordx4 v[120:123], v177, s[44:45]
	s_lshl_b64 s[44:45], s[48:49], 11
	v_or_b32_e32 v124, s44, v36
	v_mov_b32_e32 v125, s45
	v_lshl_add_u64 v[126:127], s[4:5], 0, v[124:125]
	global_load_ushort v123, v[126:127], off
	v_lshl_add_u64 v[126:127], s[8:9], 0, v[124:125]
	s_lshl_b64 s[44:45], s[48:49], 8
	global_load_ushort v174, v[126:127], off
	v_lshl_add_u64 v[126:127], s[10:11], 0, v[124:125]
	s_add_u32 s44, s16, s44
	global_load_ushort v165, v[126:127], off
	v_lshl_add_u64 v[126:127], s[6:7], 0, v[124:125]
	v_lshl_add_u64 v[124:125], s[12:13], 0, v[124:125]
	s_addc_u32 s45, s17, s45
	s_add_i32 s48, s1, 39
	global_load_ushort v169, v[126:127], off
	global_load_ushort v171, v[124:125], off
	s_nop 0
	global_load_dwordx4 v[124:127], v177, s[44:45]
	s_lshl_b64 s[44:45], s[48:49], 11
	v_or_b32_e32 v128, s44, v36
	v_mov_b32_e32 v129, s45
	s_lshl_b64 s[44:45], s[48:49], 8
	s_add_u32 s44, s16, s44
	s_addc_u32 s45, s17, s45
	s_min_i32 s0, s0, 0x1ff7
	v_lshl_add_u64 v[130:131], s[4:5], 0, v[128:129]
	s_add_i32 s48, s0, s51
	global_load_ushort v127, v[130:131], off
	v_lshl_add_u64 v[130:131], s[8:9], 0, v[128:129]
	s_lshl_b64 s[0:1], s[48:49], 11
	global_load_ushort v175, v[130:131], off
	v_lshl_add_u64 v[130:131], s[10:11], 0, v[128:129]
	v_lshl_add_u64 v[132:133], v[38:39], 0, s[0:1]
	s_lshl_b64 s[0:1], s[48:49], 8
	global_load_ushort v168, v[130:131], off
	v_lshl_add_u64 v[130:131], s[6:7], 0, v[128:129]
	v_lshl_add_u64 v[128:129], s[12:13], 0, v[128:129]
	s_add_u32 s0, s16, s0
	global_load_ushort v170, v[130:131], off
	global_load_ushort v173, v[128:129], off
	s_addc_u32 s1, s17, s1
	global_load_dwordx4 v[128:131], v177, s[44:45]
	global_load_ushort v131, v[132:133], off
	global_load_dwordx4 v[132:135], v177, s[0:1]
	s_add_i32 s48, s48, 128
	s_lshl_b64 s[44:45], s[48:49], 11
	v_or_b32_e32 v76, s44, v36
	global_load_ushort v77, v76, s[4:5]
	global_load_ushort v77, v76, s[8:9]
	global_load_ushort v77, v76, s[10:11]
	global_load_ushort v77, v76, s[6:7]
	global_load_ushort v77, v76, s[12:13]
	s_branch .LBB0_630
.LBB0_629:
	s_or_b64 exec, exec, s[0:1]
	s_add_i32 s1, s30, s41
	s_add_i32 s48, s1, 48
	s_lshl_b64 s[44:45], s[48:49], 11
	v_or_b32_e32 v0, s44, v36
	v_mov_b32_e32 v1, s45
	s_add_i32 s0, s29, s41
	v_lshl_add_u64 v[2:3], s[4:5], 0, v[0:1]
	s_add_i32 s0, s0, 48
	global_load_ushort v43, v[2:3], off
	v_lshl_add_u64 v[2:3], s[8:9], 0, v[0:1]
	s_lshl_b64 s[44:45], s[48:49], 8
	global_load_ushort v45, v[2:3], off
	v_lshl_add_u64 v[2:3], s[10:11], 0, v[0:1]
	s_add_u32 s44, s16, s44
	global_load_ushort v44, v[2:3], off
	v_lshl_add_u64 v[2:3], s[6:7], 0, v[0:1]
	v_lshl_add_u64 v[0:1], s[12:13], 0, v[0:1]
	s_addc_u32 s45, s17, s45
	s_add_i32 s48, s1, 49
	global_load_ushort v46, v[2:3], off
	global_load_ushort v49, v[0:1], off
	s_nop 0
	global_load_dwordx4 v[0:3], v177, s[44:45]
	s_lshl_b64 s[44:45], s[48:49], 11
	v_or_b32_e32 v4, s44, v36
	v_mov_b32_e32 v5, s45
	v_lshl_add_u64 v[6:7], s[4:5], 0, v[4:5]
	global_load_ushort v3, v[6:7], off
	v_lshl_add_u64 v[6:7], s[8:9], 0, v[4:5]
	s_lshl_b64 s[44:45], s[48:49], 8
	global_load_ushort v52, v[6:7], off
	v_lshl_add_u64 v[6:7], s[10:11], 0, v[4:5]
	s_add_u32 s44, s16, s44
	global_load_ushort v47, v[6:7], off
	v_lshl_add_u64 v[6:7], s[6:7], 0, v[4:5]
	v_lshl_add_u64 v[4:5], s[12:13], 0, v[4:5]
	s_addc_u32 s45, s17, s45
	s_add_i32 s48, s1, 50
	global_load_ushort v50, v[6:7], off
	global_load_ushort v53, v[4:5], off
	s_nop 0
	global_load_dwordx4 v[4:7], v177, s[44:45]
	s_lshl_b64 s[44:45], s[48:49], 11
	v_or_b32_e32 v8, s44, v36
	v_mov_b32_e32 v9, s45
	v_lshl_add_u64 v[10:11], s[4:5], 0, v[8:9]
	global_load_ushort v7, v[10:11], off
	v_lshl_add_u64 v[10:11], s[8:9], 0, v[8:9]
	s_lshl_b64 s[44:45], s[48:49], 8
	global_load_ushort v60, v[10:11], off
	v_lshl_add_u64 v[10:11], s[10:11], 0, v[8:9]
	s_add_u32 s44, s16, s44
	global_load_ushort v48, v[10:11], off
	v_lshl_add_u64 v[10:11], s[6:7], 0, v[8:9]
	v_lshl_add_u64 v[8:9], s[12:13], 0, v[8:9]
	s_addc_u32 s45, s17, s45
	s_add_i32 s48, s1, 51
	global_load_ushort v51, v[10:11], off
	global_load_ushort v55, v[8:9], off
	s_nop 0
	global_load_dwordx4 v[8:11], v177, s[44:45]
	s_lshl_b64 s[44:45], s[48:49], 11
	v_or_b32_e32 v12, s44, v36
	v_mov_b32_e32 v13, s45
	v_lshl_add_u64 v[14:15], s[4:5], 0, v[12:13]
	global_load_ushort v11, v[14:15], off
	v_lshl_add_u64 v[14:15], s[8:9], 0, v[12:13]
	s_lshl_b64 s[44:45], s[48:49], 8
	global_load_ushort v64, v[14:15], off
	v_lshl_add_u64 v[14:15], s[10:11], 0, v[12:13]
	s_add_u32 s44, s16, s44
	global_load_ushort v54, v[14:15], off
	v_lshl_add_u64 v[14:15], s[6:7], 0, v[12:13]
	v_lshl_add_u64 v[12:13], s[12:13], 0, v[12:13]
	s_addc_u32 s45, s17, s45
	s_add_i32 s48, s1, 52
	global_load_ushort v57, v[14:15], off
	global_load_ushort v58, v[12:13], off
	s_nop 0
	global_load_dwordx4 v[12:15], v177, s[44:45]
	s_lshl_b64 s[44:45], s[48:49], 11
	v_or_b32_e32 v16, s44, v36
	v_mov_b32_e32 v17, s45
	v_lshl_add_u64 v[18:19], s[4:5], 0, v[16:17]
	global_load_ushort v15, v[18:19], off
	v_lshl_add_u64 v[18:19], s[8:9], 0, v[16:17]
	s_lshl_b64 s[44:45], s[48:49], 8
	global_load_ushort v67, v[18:19], off
	v_lshl_add_u64 v[18:19], s[10:11], 0, v[16:17]
	s_add_u32 s44, s16, s44
	global_load_ushort v56, v[18:19], off
	v_lshl_add_u64 v[18:19], s[6:7], 0, v[16:17]
	v_lshl_add_u64 v[16:17], s[12:13], 0, v[16:17]
	s_addc_u32 s45, s17, s45
	s_add_i32 s48, s1, 53
	global_load_ushort v61, v[18:19], off
	global_load_ushort v63, v[16:17], off
	s_nop 0
	global_load_dwordx4 v[16:19], v177, s[44:45]
	s_lshl_b64 s[44:45], s[48:49], 11
	v_or_b32_e32 v20, s44, v36
	v_mov_b32_e32 v21, s45
	v_lshl_add_u64 v[22:23], s[4:5], 0, v[20:21]
	global_load_ushort v19, v[22:23], off
	v_lshl_add_u64 v[22:23], s[8:9], 0, v[20:21]
	s_lshl_b64 s[44:45], s[48:49], 8
	global_load_ushort v72, v[22:23], off
	v_lshl_add_u64 v[22:23], s[10:11], 0, v[20:21]
	s_add_u32 s44, s16, s44
	global_load_ushort v59, v[22:23], off
	v_lshl_add_u64 v[22:23], s[6:7], 0, v[20:21]
	v_lshl_add_u64 v[20:21], s[12:13], 0, v[20:21]
	s_addc_u32 s45, s17, s45
	s_add_i32 s48, s1, 54
	global_load_ushort v62, v[22:23], off
	global_load_ushort v66, v[20:21], off
	s_nop 0
	global_load_dwordx4 v[20:23], v177, s[44:45]
	s_lshl_b64 s[44:45], s[48:49], 11
	v_or_b32_e32 v24, s44, v36
	v_mov_b32_e32 v25, s45
	v_lshl_add_u64 v[26:27], s[4:5], 0, v[24:25]
	global_load_ushort v23, v[26:27], off
	v_lshl_add_u64 v[26:27], s[8:9], 0, v[24:25]
	s_lshl_b64 s[44:45], s[48:49], 8
	global_load_ushort v74, v[26:27], off
	v_lshl_add_u64 v[26:27], s[10:11], 0, v[24:25]
	s_add_u32 s44, s16, s44
	global_load_ushort v65, v[26:27], off
	v_lshl_add_u64 v[26:27], s[6:7], 0, v[24:25]
	v_lshl_add_u64 v[24:25], s[12:13], 0, v[24:25]
	s_addc_u32 s45, s17, s45
	s_add_i32 s48, s1, 55
	global_load_ushort v69, v[26:27], off
	global_load_ushort v71, v[24:25], off
	s_nop 0
	global_load_dwordx4 v[24:27], v177, s[44:45]
	s_lshl_b64 s[44:45], s[48:49], 11
	v_or_b32_e32 v28, s44, v36
	v_mov_b32_e32 v29, s45
	s_lshl_b64 s[44:45], s[48:49], 8
	s_add_u32 s44, s16, s44
	s_addc_u32 s45, s17, s45
	s_min_i32 s0, s0, 0x1ff7
	v_lshl_add_u64 v[30:31], s[4:5], 0, v[28:29]
	s_add_i32 s48, s0, s51
	global_load_ushort v27, v[30:31], off
	v_lshl_add_u64 v[30:31], s[8:9], 0, v[28:29]
	s_lshl_b64 s[0:1], s[48:49], 11
	global_load_ushort v75, v[30:31], off
	v_lshl_add_u64 v[30:31], s[10:11], 0, v[28:29]
	v_lshl_add_u64 v[32:33], v[38:39], 0, s[0:1]
	s_lshl_b64 s[0:1], s[48:49], 8
	global_load_ushort v68, v[30:31], off
	v_lshl_add_u64 v[30:31], s[6:7], 0, v[28:29]
	v_lshl_add_u64 v[28:29], s[12:13], 0, v[28:29]
	s_add_u32 s0, s16, s0
	global_load_ushort v70, v[30:31], off
	global_load_ushort v73, v[28:29], off
	s_addc_u32 s1, s17, s1
	global_load_dwordx4 v[28:31], v177, s[44:45]
	global_load_ushort v31, v[32:33], off
	s_add_i32 s41, s41, 16
	global_load_dwordx4 v[32:35], v177, s[0:1]
	s_add_i32 s48, s48, 128
	s_lshl_b64 s[44:45], s[48:49], 11
	v_or_b32_e32 v76, s44, v36
	global_load_ushort v77, v76, s[4:5]
	global_load_ushort v77, v76, s[8:9]
	global_load_ushort v77, v76, s[10:11]
	global_load_ushort v77, v76, s[6:7]
	global_load_ushort v77, v76, s[12:13]
	s_waitcnt lgkmcnt(0)
	s_barrier
	s_add_i32 s40, s40, 1
	s_cmpk_eq_i32 s41, 0xfe0
	s_cbranch_scc1 .LBB0_646
	s_waitcnt vmcnt(55)
	v_lshlrev_b32_e32 v134, 16, v149
	s_and_b32 s0, s40, 1
	v_lshlrev_b32_e32 v133, 16, v145
	v_lshlrev_b32_e32 v135, 16, v146
	v_add_f32_e32 v145, -1.0, v134
	s_or_b32 s0, s0, s20
	v_mul_f32_e32 v135, 0xbfb8aa3b, v135
	v_fma_f32 v145, v42, v145, 1.0
	s_mulk_i32 s0, 0x6080
	v_exp_f32_e32 v135, v135
	v_mul_f32_e32 v145, v145, v133
	v_mul_f32_e32 v133, v41, v133
	s_add_i32 s42, s0, 0
	v_mul_f32_e32 v100, v100, v133
	v_lshlrev_b32_e32 v133, 16, v152
	v_mul_f32_e32 v146, v41, v133
	s_add_i32 s0, s42, s18
	v_mul_f32_e32 v104, v146, v104
	v_lshl_add_u32 v149, v37, 2, s0
	v_mul_f32_e32 v100, v100, v134
	v_mul_f32_e32 v146, v104, v135
	ds_write2st64_b32 v149, v100, v145 offset0:32 offset1:48
	v_lshlrev_b32_e32 v100, 16, v143
	v_lshlrev_b32_e32 v134, 16, v144
	ds_write2st64_b32 v149, v146, v135 offset1:16
	ds_write2st64_b32 v149, v100, v134 offset0:64 offset1:80
	s_and_saveexec_b64 s[0:1], s[2:3]
	s_add_i32 s44, s42, s37
	v_mov_b32_e32 v100, v101
	v_mov_b32_e32 v101, v102
	v_mov_b32_e32 v102, s44
	ds_write_b64 v102, v[100:101] offset:24576
	s_or_b64 exec, exec, s[0:1]
	v_lshlrev_b32_e32 v102, 16, v160
	v_mul_f32_e32 v100, v41, v102
	v_mul_f32_e32 v100, v100, v108
	v_lshlrev_b32_e32 v108, 16, v150
	v_mul_f32_e32 v108, 0xbfb8aa3b, v108
	v_lshlrev_b32_e32 v101, 16, v153
	v_exp_f32_e32 v108, v108
	v_add_f32_e32 v134, -1.0, v101
	v_fma_f32 v134, v42, v134, 1.0
	s_add_i32 s0, s42, s19
	v_mul_f32_e32 v133, v134, v133
	v_lshl_add_u32 v135, v37, 2, s0
	v_mul_f32_e32 v101, v104, v101
	v_mul_f32_e32 v134, v100, v108
	ds_write2st64_b32 v135, v101, v133 offset0:32 offset1:48
	v_lshlrev_b32_e32 v101, 16, v103
	v_lshlrev_b32_e32 v103, 16, v147
	ds_write2st64_b32 v135, v134, v108 offset1:16
	ds_write2st64_b32 v135, v101, v103 offset0:64 offset1:80
	s_and_saveexec_b64 s[0:1], s[2:3]
	s_add_i32 s44, s42, s36
	v_mov_b32_e32 v104, v105
	v_mov_b32_e32 v105, v106
	v_mov_b32_e32 v101, s44
	ds_write_b64 v101, v[104:105] offset:24576
	s_or_b64 exec, exec, s[0:1]
	v_lshlrev_b32_e32 v105, 16, v151
	v_mul_f32_e32 v105, 0xbfb8aa3b, v105
	v_lshlrev_b32_e32 v104, 16, v155
	v_exp_f32_e32 v105, v105
	v_lshlrev_b32_e32 v103, 16, v164
	v_add_f32_e32 v106, -1.0, v104
	v_mul_f32_e32 v101, v41, v103
	v_fma_f32 v106, v42, v106, 1.0
	s_add_i32 s0, s42, s21
	v_mul_f32_e32 v101, v101, v112
	v_mul_f32_e32 v102, v106, v102
	v_lshl_add_u32 v108, v37, 2, s0
	v_mul_f32_e32 v100, v100, v104
	v_mul_f32_e32 v106, v101, v105
	ds_write2st64_b32 v108, v100, v102 offset0:32 offset1:48
	v_lshlrev_b32_e32 v100, 16, v107
	v_lshlrev_b32_e32 v102, 16, v148
	ds_write2st64_b32 v108, v106, v105 offset1:16
	ds_write2st64_b32 v108, v100, v102 offset0:64 offset1:80
	s_and_saveexec_b64 s[0:1], s[2:3]
	s_add_i32 s44, s42, s35
	v_mov_b32_e32 v104, v109
	v_mov_b32_e32 v105, v110
	v_mov_b32_e32 v100, s44
	ds_write_b64 v100, v[104:105] offset:24576
	s_or_b64 exec, exec, s[0:1]
	v_lshlrev_b32_e32 v105, 16, v157
	v_mul_f32_e32 v105, 0xbfb8aa3b, v105
	v_lshlrev_b32_e32 v104, 16, v158
	v_exp_f32_e32 v105, v105
	v_lshlrev_b32_e32 v102, 16, v167
	v_add_f32_e32 v106, -1.0, v104
	v_mul_f32_e32 v100, v41, v102
	v_fma_f32 v106, v42, v106, 1.0
	s_add_i32 s0, s42, s22
	v_mul_f32_e32 v100, v100, v116
	v_mul_f32_e32 v103, v106, v103
	v_lshl_add_u32 v107, v37, 2, s0
	v_mul_f32_e32 v101, v101, v104
	v_mul_f32_e32 v106, v100, v105
	ds_write2st64_b32 v107, v101, v103 offset0:32 offset1:48
	v_lshlrev_b32_e32 v101, 16, v111
	v_lshlrev_b32_e32 v103, 16, v154
	ds_write2st64_b32 v107, v106, v105 offset1:16
	ds_write2st64_b32 v107, v101, v103 offset0:64 offset1:80
	s_and_saveexec_b64 s[0:1], s[2:3]
	s_add_i32 s44, s42, s34
	v_mov_b32_e32 v104, v113
	v_mov_b32_e32 v105, v114
	v_mov_b32_e32 v101, s44
	ds_write_b64 v101, v[104:105] offset:24576
	s_or_b64 exec, exec, s[0:1]
	v_lshlrev_b32_e32 v105, 16, v161
	v_mul_f32_e32 v105, 0xbfb8aa3b, v105
	v_lshlrev_b32_e32 v104, 16, v163
	v_exp_f32_e32 v105, v105
	v_lshlrev_b32_e32 v103, 16, v172
	v_add_f32_e32 v106, -1.0, v104
	v_mul_f32_e32 v101, v41, v103
	v_fma_f32 v106, v42, v106, 1.0
	s_add_i32 s0, s42, s23
	v_mul_f32_e32 v101, v101, v120
	v_mul_f32_e32 v102, v106, v102
	v_lshl_add_u32 v107, v37, 2, s0
	v_mul_f32_e32 v100, v100, v104
	v_mul_f32_e32 v106, v101, v105
	ds_write2st64_b32 v107, v100, v102 offset0:32 offset1:48
	v_lshlrev_b32_e32 v100, 16, v115
	v_lshlrev_b32_e32 v102, 16, v156
	ds_write2st64_b32 v107, v106, v105 offset1:16
	ds_write2st64_b32 v107, v100, v102 offset0:64 offset1:80
	s_and_saveexec_b64 s[0:1], s[2:3]
	s_add_i32 s44, s42, s33
	v_mov_b32_e32 v104, v117
	v_mov_b32_e32 v105, v118
	v_mov_b32_e32 v100, s44
	ds_write_b64 v100, v[104:105] offset:24576
	s_or_b64 exec, exec, s[0:1]
	v_lshlrev_b32_e32 v105, 16, v162
	v_mul_f32_e32 v105, 0xbfb8aa3b, v105
	v_lshlrev_b32_e32 v104, 16, v166
	v_exp_f32_e32 v105, v105
	v_lshlrev_b32_e32 v102, 16, v174
	v_add_f32_e32 v106, -1.0, v104
	v_mul_f32_e32 v100, v41, v102
	v_fma_f32 v106, v42, v106, 1.0
	s_add_i32 s0, s42, s24
	v_mul_f32_e32 v100, v100, v124
	v_mul_f32_e32 v103, v106, v103
	v_lshl_add_u32 v107, v37, 2, s0
	v_mul_f32_e32 v101, v101, v104
	v_mul_f32_e32 v106, v100, v105
	ds_write2st64_b32 v107, v101, v103 offset0:32 offset1:48
	v_lshlrev_b32_e32 v101, 16, v119
	v_lshlrev_b32_e32 v103, 16, v159
	ds_write2st64_b32 v107, v106, v105 offset1:16
	ds_write2st64_b32 v107, v101, v103 offset0:64 offset1:80
	s_and_saveexec_b64 s[0:1], s[2:3]
	s_add_i32 s44, s42, s31
	v_mov_b32_e32 v104, v121
	v_mov_b32_e32 v105, v122
	v_mov_b32_e32 v101, s44
	ds_write_b64 v101, v[104:105] offset:24576
	s_or_b64 exec, exec, s[0:1]
	v_lshlrev_b32_e32 v105, 16, v169
	v_mul_f32_e32 v105, 0xbfb8aa3b, v105
	v_lshlrev_b32_e32 v104, 16, v171
	v_exp_f32_e32 v105, v105
	v_lshlrev_b32_e32 v103, 16, v175
	v_add_f32_e32 v106, -1.0, v104
	v_mul_f32_e32 v101, v41, v103
	v_fma_f32 v106, v42, v106, 1.0
	s_add_i32 s0, s42, s26
	v_mul_f32_e32 v101, v101, v128
	v_mul_f32_e32 v102, v106, v102
	v_lshl_add_u32 v107, v37, 2, s0
	v_mul_f32_e32 v100, v100, v104
	v_mul_f32_e32 v106, v101, v105
	ds_write2st64_b32 v107, v100, v102 offset0:32 offset1:48
	v_lshlrev_b32_e32 v100, 16, v123
	v_lshlrev_b32_e32 v102, 16, v165
	ds_write2st64_b32 v107, v106, v105 offset1:16
	ds_write2st64_b32 v107, v100, v102 offset0:64 offset1:80
	s_and_saveexec_b64 s[0:1], s[2:3]
	s_add_i32 s44, s42, s28
	v_mov_b32_e32 v104, v125
	v_mov_b32_e32 v105, v126
	v_mov_b32_e32 v100, s44
	ds_write_b64 v100, v[104:105] offset:24576
	s_or_b64 exec, exec, s[0:1]
	v_lshlrev_b32_e32 v104, 16, v170
	v_mul_f32_e32 v104, 0xbfb8aa3b, v104
	v_exp_f32_e32 v104, v104
	v_lshlrev_b32_e32 v100, 16, v131
	v_lshlrev_b32_e32 v102, 16, v173
	v_mul_f32_e32 v100, v41, v100
	v_add_f32_e32 v105, -1.0, v102
	v_mul_f32_e32 v100, v100, v132
	v_fma_f32 v105, v42, v105, 1.0
	s_add_i32 s0, s42, s27
	v_mul_f32_e32 v103, v105, v103
	v_mul_f32_e32 v100, v100, v104
	v_lshl_add_u32 v105, v37, 2, s0
	ds_write2st64_b32 v105, v100, v104 offset1:16
	v_mul_f32_e32 v100, v101, v102
	ds_write2st64_b32 v105, v100, v103 offset0:32 offset1:48
	v_lshlrev_b32_e32 v100, 16, v127
	v_lshlrev_b32_e32 v101, 16, v168
	ds_write2st64_b32 v105, v100, v101 offset0:64 offset1:80
	s_and_saveexec_b64 s[0:1], s[2:3]
	s_cbranch_execz .Lst_B_load
	s_add_i32 s42, s42, s25
	v_mov_b32_e32 v100, v129
	v_mov_b32_e32 v101, v130
	v_mov_b32_e32 v102, s42
	ds_write_b64 v102, v[100:101] offset:24576
	s_branch .Lst_B_load
.Lst_B_load:
	s_or_b64 exec, exec, s[0:1]
	s_add_i32 s1, s30, s41
	s_add_i32 s48, s1, 48
	s_lshl_b64 s[44:45], s[48:49], 11
	v_or_b32_e32 v100, s44, v36
	v_mov_b32_e32 v101, s45
	s_add_i32 s0, s29, s41
	v_lshl_add_u64 v[102:103], s[4:5], 0, v[100:101]
	s_add_i32 s0, s0, 48
	global_load_ushort v143, v[102:103], off
	v_lshl_add_u64 v[102:103], s[8:9], 0, v[100:101]
	s_lshl_b64 s[44:45], s[48:49], 8
	global_load_ushort v145, v[102:103], off
	v_lshl_add_u64 v[102:103], s[10:11], 0, v[100:101]
	s_add_u32 s44, s16, s44
	global_load_ushort v144, v[102:103], off
	v_lshl_add_u64 v[102:103], s[6:7], 0, v[100:101]
	v_lshl_add_u64 v[100:101], s[12:13], 0, v[100:101]
	s_addc_u32 s45, s17, s45
	s_add_i32 s48, s1, 49
	global_load_ushort v146, v[102:103], off
	global_load_ushort v149, v[100:101], off
	s_nop 0
	global_load_dwordx4 v[100:103], v177, s[44:45]
	s_lshl_b64 s[44:45], s[48:49], 11
	v_or_b32_e32 v104, s44, v36
	v_mov_b32_e32 v105, s45
	v_lshl_add_u64 v[106:107], s[4:5], 0, v[104:105]
	global_load_ushort v103, v[106:107], off
	v_lshl_add_u64 v[106:107], s[8:9], 0, v[104:105]
	s_lshl_b64 s[44:45], s[48:49], 8
	global_load_ushort v152, v[106:107], off
	v_lshl_add_u64 v[106:107], s[10:11], 0, v[104:105]
	s_add_u32 s44, s16, s44
	global_load_ushort v147, v[106:107], off
	v_lshl_add_u64 v[106:107], s[6:7], 0, v[104:105]
	v_lshl_add_u64 v[104:105], s[12:13], 0, v[104:105]
	s_addc_u32 s45, s17, s45
	s_add_i32 s48, s1, 50
	global_load_ushort v150, v[106:107], off
	global_load_ushort v153, v[104:105], off
	s_nop 0
	global_load_dwordx4 v[104:107], v177, s[44:45]
	s_lshl_b64 s[44:45], s[48:49], 11
	v_or_b32_e32 v108, s44, v36
	v_mov_b32_e32 v109, s45
	v_lshl_add_u64 v[110:111], s[4:5], 0, v[108:109]
	global_load_ushort v107, v[110:111], off
	v_lshl_add_u64 v[110:111], s[8:9], 0, v[108:109]
	s_lshl_b64 s[44:45], s[48:49], 8
	global_load_ushort v160, v[110:111], off
	v_lshl_add_u64 v[110:111], s[10:11], 0, v[108:109]
	s_add_u32 s44, s16, s44
	global_load_ushort v148, v[110:111], off
	v_lshl_add_u64 v[110:111], s[6:7], 0, v[108:109]
	v_lshl_add_u64 v[108:109], s[12:13], 0, v[108:109]
	s_addc_u32 s45, s17, s45
	s_add_i32 s48, s1, 51
	global_load_ushort v151, v[110:111], off
	global_load_ushort v155, v[108:109], off
	s_nop 0
	global_load_dwordx4 v[108:111], v177, s[44:45]
	s_lshl_b64 s[44:45], s[48:49], 11
	v_or_b32_e32 v112, s44, v36
	v_mov_b32_e32 v113, s45
	v_lshl_add_u64 v[114:115], s[4:5], 0, v[112:113]
	global_load_ushort v111, v[114:115], off
	v_lshl_add_u64 v[114:115], s[8:9], 0, v[112:113]
	s_lshl_b64 s[44:45], s[48:49], 8
	global_load_ushort v164, v[114:115], off
	v_lshl_add_u64 v[114:115], s[10:11], 0, v[112:113]
	s_add_u32 s44, s16, s44
	global_load_ushort v154, v[114:115], off
	v_lshl_add_u64 v[114:115], s[6:7], 0, v[112:113]
	v_lshl_add_u64 v[112:113], s[12:13], 0, v[112:113]
	s_addc_u32 s45, s17, s45
	s_add_i32 s48, s1, 52
	global_load_ushort v157, v[114:115], off
	global_load_ushort v158, v[112:113], off
	s_nop 0
	global_load_dwordx4 v[112:115], v177, s[44:45]
	s_lshl_b64 s[44:45], s[48:49], 11
	v_or_b32_e32 v116, s44, v36
	v_mov_b32_e32 v117, s45
	v_lshl_add_u64 v[118:119], s[4:5], 0, v[116:117]
	global_load_ushort v115, v[118:119], off
	v_lshl_add_u64 v[118:119], s[8:9], 0, v[116:117]
	s_lshl_b64 s[44:45], s[48:49], 8
	global_load_ushort v167, v[118:119], off
	v_lshl_add_u64 v[118:119], s[10:11], 0, v[116:117]
	s_add_u32 s44, s16, s44
	global_load_ushort v156, v[118:119], off
	v_lshl_add_u64 v[118:119], s[6:7], 0, v[116:117]
	v_lshl_add_u64 v[116:117], s[12:13], 0, v[116:117]
	s_addc_u32 s45, s17, s45
	s_add_i32 s48, s1, 53
	global_load_ushort v161, v[118:119], off
	global_load_ushort v163, v[116:117], off
	s_nop 0
	global_load_dwordx4 v[116:119], v177, s[44:45]
	s_lshl_b64 s[44:45], s[48:49], 11
	v_or_b32_e32 v120, s44, v36
	v_mov_b32_e32 v121, s45
	v_lshl_add_u64 v[122:123], s[4:5], 0, v[120:121]
	global_load_ushort v119, v[122:123], off
	v_lshl_add_u64 v[122:123], s[8:9], 0, v[120:121]
	s_lshl_b64 s[44:45], s[48:49], 8
	global_load_ushort v172, v[122:123], off
	v_lshl_add_u64 v[122:123], s[10:11], 0, v[120:121]
	s_add_u32 s44, s16, s44
	global_load_ushort v159, v[122:123], off
	v_lshl_add_u64 v[122:123], s[6:7], 0, v[120:121]
	v_lshl_add_u64 v[120:121], s[12:13], 0, v[120:121]
	s_addc_u32 s45, s17, s45
	s_add_i32 s48, s1, 54
	global_load_ushort v162, v[122:123], off
	global_load_ushort v166, v[120:121], off
	s_nop 0
	global_load_dwordx4 v[120:123], v177, s[44:45]
	s_lshl_b64 s[44:45], s[48:49], 11
	v_or_b32_e32 v124, s44, v36
	v_mov_b32_e32 v125, s45
	v_lshl_add_u64 v[126:127], s[4:5], 0, v[124:125]
	global_load_ushort v123, v[126:127], off
	v_lshl_add_u64 v[126:127], s[8:9], 0, v[124:125]
	s_lshl_b64 s[44:45], s[48:49], 8
	global_load_ushort v174, v[126:127], off
	v_lshl_add_u64 v[126:127], s[10:11], 0, v[124:125]
	s_add_u32 s44, s16, s44
	global_load_ushort v165, v[126:127], off
	v_lshl_add_u64 v[126:127], s[6:7], 0, v[124:125]
	v_lshl_add_u64 v[124:125], s[12:13], 0, v[124:125]
	s_addc_u32 s45, s17, s45
	s_add_i32 s48, s1, 55
	global_load_ushort v169, v[126:127], off
	global_load_ushort v171, v[124:125], off
	s_nop 0
	global_load_dwordx4 v[124:127], v177, s[44:45]
	s_lshl_b64 s[44:45], s[48:49], 11
	v_or_b32_e32 v128, s44, v36
	v_mov_b32_e32 v129, s45
	s_lshl_b64 s[44:45], s[48:49], 8
	s_add_u32 s44, s16, s44
	s_addc_u32 s45, s17, s45
	s_min_i32 s0, s0, 0x1ff7
	v_lshl_add_u64 v[130:131], s[4:5], 0, v[128:129]
	s_add_i32 s48, s0, s51
	global_load_ushort v127, v[130:131], off
	v_lshl_add_u64 v[130:131], s[8:9], 0, v[128:129]
	s_lshl_b64 s[0:1], s[48:49], 11
	global_load_ushort v175, v[130:131], off
	v_lshl_add_u64 v[130:131], s[10:11], 0, v[128:129]
	v_lshl_add_u64 v[132:133], v[38:39], 0, s[0:1]
	s_lshl_b64 s[0:1], s[48:49], 8
	global_load_ushort v168, v[130:131], off
	v_lshl_add_u64 v[130:131], s[6:7], 0, v[128:129]
	v_lshl_add_u64 v[128:129], s[12:13], 0, v[128:129]
	s_add_u32 s0, s16, s0
	global_load_ushort v170, v[130:131], off
	global_load_ushort v173, v[128:129], off
	s_addc_u32 s1, s17, s1
	global_load_dwordx4 v[128:131], v177, s[44:45]
	global_load_ushort v131, v[132:133], off
	s_add_i32 s41, s41, 16
	global_load_dwordx4 v[132:135], v177, s[0:1]
	s_add_i32 s48, s48, 128
	s_lshl_b64 s[44:45], s[48:49], 11
	v_or_b32_e32 v76, s44, v36
	global_load_ushort v77, v76, s[4:5]
	global_load_ushort v77, v76, s[8:9]
	global_load_ushort v77, v76, s[10:11]
	global_load_ushort v77, v76, s[6:7]
	global_load_ushort v77, v76, s[12:13]
	s_waitcnt lgkmcnt(0)
	s_barrier
	s_add_i32 s40, s40, 1
	s_cmpk_eq_i32 s41, 0xfe0
	s_cbranch_scc1 .LBB0_646
.LBB0_630:
	s_waitcnt vmcnt(55)
	v_lshlrev_b32_e32 v34, 16, v49
	s_and_b32 s0, s40, 1
	v_lshlrev_b32_e32 v33, 16, v45
	v_lshlrev_b32_e32 v35, 16, v46
	v_add_f32_e32 v45, -1.0, v34
	s_or_b32 s0, s0, s20
	v_mul_f32_e32 v35, 0xbfb8aa3b, v35
	v_fma_f32 v45, v42, v45, 1.0
	s_mulk_i32 s0, 0x6080
	v_exp_f32_e32 v35, v35
	v_mul_f32_e32 v45, v45, v33
	v_mul_f32_e32 v33, v41, v33
	s_add_i32 s42, s0, 0
	v_mul_f32_e32 v0, v0, v33
	v_lshlrev_b32_e32 v33, 16, v52
	v_mul_f32_e32 v46, v41, v33
	s_add_i32 s0, s42, s18
	v_mul_f32_e32 v4, v46, v4
	v_lshl_add_u32 v49, v37, 2, s0
	v_mul_f32_e32 v0, v0, v34
	v_mul_f32_e32 v46, v4, v35
	ds_write2st64_b32 v49, v0, v45 offset0:32 offset1:48
	v_lshlrev_b32_e32 v0, 16, v43
	v_lshlrev_b32_e32 v34, 16, v44
	ds_write2st64_b32 v49, v46, v35 offset1:16
	ds_write2st64_b32 v49, v0, v34 offset0:64 offset1:80
	s_and_saveexec_b64 s[0:1], s[2:3]
	s_add_i32 s44, s42, s37
	v_mov_b32_e32 v0, v1
	v_mov_b32_e32 v1, v2
	v_mov_b32_e32 v2, s44
	ds_write_b64 v2, v[0:1] offset:24576
	s_or_b64 exec, exec, s[0:1]
	v_lshlrev_b32_e32 v2, 16, v60
	v_mul_f32_e32 v0, v41, v2
	v_mul_f32_e32 v0, v0, v8
	v_lshlrev_b32_e32 v8, 16, v50
	v_mul_f32_e32 v8, 0xbfb8aa3b, v8
	v_lshlrev_b32_e32 v1, 16, v53
	v_exp_f32_e32 v8, v8
	v_add_f32_e32 v34, -1.0, v1
	v_fma_f32 v34, v42, v34, 1.0
	s_add_i32 s0, s42, s19
	v_mul_f32_e32 v33, v34, v33
	v_lshl_add_u32 v35, v37, 2, s0
	v_mul_f32_e32 v1, v4, v1
	v_mul_f32_e32 v34, v0, v8
	ds_write2st64_b32 v35, v1, v33 offset0:32 offset1:48
	v_lshlrev_b32_e32 v1, 16, v3
	v_lshlrev_b32_e32 v3, 16, v47
	ds_write2st64_b32 v35, v34, v8 offset1:16
	ds_write2st64_b32 v35, v1, v3 offset0:64 offset1:80
	s_and_saveexec_b64 s[0:1], s[2:3]
	s_add_i32 s44, s42, s36
	v_mov_b32_e32 v4, v5
	v_mov_b32_e32 v5, v6
	v_mov_b32_e32 v1, s44
	ds_write_b64 v1, v[4:5] offset:24576
	s_or_b64 exec, exec, s[0:1]
	v_lshlrev_b32_e32 v5, 16, v51
	v_mul_f32_e32 v5, 0xbfb8aa3b, v5
	v_lshlrev_b32_e32 v4, 16, v55
	v_exp_f32_e32 v5, v5
	v_lshlrev_b32_e32 v3, 16, v64
	v_add_f32_e32 v6, -1.0, v4
	v_mul_f32_e32 v1, v41, v3
	v_fma_f32 v6, v42, v6, 1.0
	s_add_i32 s0, s42, s21
	v_mul_f32_e32 v1, v1, v12
	v_mul_f32_e32 v2, v6, v2
	v_lshl_add_u32 v8, v37, 2, s0
	v_mul_f32_e32 v0, v0, v4
	v_mul_f32_e32 v6, v1, v5
	ds_write2st64_b32 v8, v0, v2 offset0:32 offset1:48
	v_lshlrev_b32_e32 v0, 16, v7
	v_lshlrev_b32_e32 v2, 16, v48
	ds_write2st64_b32 v8, v6, v5 offset1:16
	ds_write2st64_b32 v8, v0, v2 offset0:64 offset1:80
	s_and_saveexec_b64 s[0:1], s[2:3]
	s_add_i32 s44, s42, s35
	v_mov_b32_e32 v4, v9
	v_mov_b32_e32 v5, v10
	v_mov_b32_e32 v0, s44
	ds_write_b64 v0, v[4:5] offset:24576
	s_or_b64 exec, exec, s[0:1]
	v_lshlrev_b32_e32 v5, 16, v57
	v_mul_f32_e32 v5, 0xbfb8aa3b, v5
	v_lshlrev_b32_e32 v4, 16, v58
	v_exp_f32_e32 v5, v5
	v_lshlrev_b32_e32 v2, 16, v67
	v_add_f32_e32 v6, -1.0, v4
	v_mul_f32_e32 v0, v41, v2
	v_fma_f32 v6, v42, v6, 1.0
	s_add_i32 s0, s42, s22
	v_mul_f32_e32 v0, v0, v16
	v_mul_f32_e32 v3, v6, v3
	v_lshl_add_u32 v7, v37, 2, s0
	v_mul_f32_e32 v1, v1, v4
	v_mul_f32_e32 v6, v0, v5
	ds_write2st64_b32 v7, v1, v3 offset0:32 offset1:48
	v_lshlrev_b32_e32 v1, 16, v11
	v_lshlrev_b32_e32 v3, 16, v54
	ds_write2st64_b32 v7, v6, v5 offset1:16
	ds_write2st64_b32 v7, v1, v3 offset0:64 offset1:80
	s_and_saveexec_b64 s[0:1], s[2:3]
	s_add_i32 s44, s42, s34
	v_mov_b32_e32 v4, v13
	v_mov_b32_e32 v5, v14
	v_mov_b32_e32 v1, s44
	ds_write_b64 v1, v[4:5] offset:24576
	s_or_b64 exec, exec, s[0:1]
	v_lshlrev_b32_e32 v5, 16, v61
	v_mul_f32_e32 v5, 0xbfb8aa3b, v5
	v_lshlrev_b32_e32 v4, 16, v63
	v_exp_f32_e32 v5, v5
	v_lshlrev_b32_e32 v3, 16, v72
	v_add_f32_e32 v6, -1.0, v4
	v_mul_f32_e32 v1, v41, v3
	v_fma_f32 v6, v42, v6, 1.0
	s_add_i32 s0, s42, s23
	v_mul_f32_e32 v1, v1, v20
	v_mul_f32_e32 v2, v6, v2
	v_lshl_add_u32 v7, v37, 2, s0
	v_mul_f32_e32 v0, v0, v4
	v_mul_f32_e32 v6, v1, v5
	ds_write2st64_b32 v7, v0, v2 offset0:32 offset1:48
	v_lshlrev_b32_e32 v0, 16, v15
	v_lshlrev_b32_e32 v2, 16, v56
	ds_write2st64_b32 v7, v6, v5 offset1:16
	ds_write2st64_b32 v7, v0, v2 offset0:64 offset1:80
	s_and_saveexec_b64 s[0:1], s[2:3]
	s_add_i32 s44, s42, s33
	v_mov_b32_e32 v4, v17
	v_mov_b32_e32 v5, v18
	v_mov_b32_e32 v0, s44
	ds_write_b64 v0, v[4:5] offset:24576
	s_or_b64 exec, exec, s[0:1]
	v_lshlrev_b32_e32 v5, 16, v62
	v_mul_f32_e32 v5, 0xbfb8aa3b, v5
	v_lshlrev_b32_e32 v4, 16, v66
	v_exp_f32_e32 v5, v5
	v_lshlrev_b32_e32 v2, 16, v74
	v_add_f32_e32 v6, -1.0, v4
	v_mul_f32_e32 v0, v41, v2
	v_fma_f32 v6, v42, v6, 1.0
	s_add_i32 s0, s42, s24
	v_mul_f32_e32 v0, v0, v24
	v_mul_f32_e32 v3, v6, v3
	v_lshl_add_u32 v7, v37, 2, s0
	v_mul_f32_e32 v1, v1, v4
	v_mul_f32_e32 v6, v0, v5
	ds_write2st64_b32 v7, v1, v3 offset0:32 offset1:48
	v_lshlrev_b32_e32 v1, 16, v19
	v_lshlrev_b32_e32 v3, 16, v59
	ds_write2st64_b32 v7, v6, v5 offset1:16
	ds_write2st64_b32 v7, v1, v3 offset0:64 offset1:80
	s_and_saveexec_b64 s[0:1], s[2:3]
	s_add_i32 s44, s42, s31
	v_mov_b32_e32 v4, v21
	v_mov_b32_e32 v5, v22
	v_mov_b32_e32 v1, s44
	ds_write_b64 v1, v[4:5] offset:24576
	s_or_b64 exec, exec, s[0:1]
	v_lshlrev_b32_e32 v5, 16, v69
	v_mul_f32_e32 v5, 0xbfb8aa3b, v5
	v_lshlrev_b32_e32 v4, 16, v71
	v_exp_f32_e32 v5, v5
	v_lshlrev_b32_e32 v3, 16, v75
	v_add_f32_e32 v6, -1.0, v4
	v_mul_f32_e32 v1, v41, v3
	v_fma_f32 v6, v42, v6, 1.0
	s_add_i32 s0, s42, s26
	v_mul_f32_e32 v1, v1, v28
	v_mul_f32_e32 v2, v6, v2
	v_lshl_add_u32 v7, v37, 2, s0
	v_mul_f32_e32 v0, v0, v4
	v_mul_f32_e32 v6, v1, v5
	ds_write2st64_b32 v7, v0, v2 offset0:32 offset1:48
	v_lshlrev_b32_e32 v0, 16, v23
	v_lshlrev_b32_e32 v2, 16, v65
	ds_write2st64_b32 v7, v6, v5 offset1:16
	ds_write2st64_b32 v7, v0, v2 offset0:64 offset1:80
	s_and_saveexec_b64 s[0:1], s[2:3]
	s_add_i32 s44, s42, s28
	v_mov_b32_e32 v4, v25
	v_mov_b32_e32 v5, v26
	v_mov_b32_e32 v0, s44
	ds_write_b64 v0, v[4:5] offset:24576
	s_or_b64 exec, exec, s[0:1]
	v_lshlrev_b32_e32 v4, 16, v70
	v_mul_f32_e32 v4, 0xbfb8aa3b, v4
	v_exp_f32_e32 v4, v4
	v_lshlrev_b32_e32 v0, 16, v31
	v_lshlrev_b32_e32 v2, 16, v73
	v_mul_f32_e32 v0, v41, v0
	v_add_f32_e32 v5, -1.0, v2
	v_mul_f32_e32 v0, v0, v32
	v_fma_f32 v5, v42, v5, 1.0
	s_add_i32 s0, s42, s27
	v_mul_f32_e32 v3, v5, v3
	v_mul_f32_e32 v0, v0, v4
	v_lshl_add_u32 v5, v37, 2, s0
	ds_write2st64_b32 v5, v0, v4 offset1:16
	v_mul_f32_e32 v0, v1, v2
	ds_write2st64_b32 v5, v0, v3 offset0:32 offset1:48
	v_lshlrev_b32_e32 v0, 16, v27
	v_lshlrev_b32_e32 v1, 16, v68
	ds_write2st64_b32 v5, v0, v1 offset0:64 offset1:80
	s_and_saveexec_b64 s[0:1], s[2:3]
	s_cbranch_execz .LBB0_629
	s_add_i32 s42, s42, s25
	v_mov_b32_e32 v0, v29
	v_mov_b32_e32 v1, v30
	v_mov_b32_e32 v2, s42
	ds_write_b64 v2, v[0:1] offset:24576
	s_branch .LBB0_629
